# type-B workgroups run their attention-gate GEMM unit first and only then wait for the P2-P3 barrier release (split barrier), conv tile slots retuned (table 0x5154, reversal 0x04)
# baseline (speedup 1.0000x reference)
.LBB0_308:
	s_lshl_b32 s8, s33, 8
	s_add_u32 s8, s24, s8
	s_addc_u32 s9, s25, 0
	v_mov_b32_e32 v2, 0x1000
	v_mov_b32_e32 v4, 1
	global_atomic_add v4, v2, v4, s[8:9] offset:1024 sc0
	v_cvt_f32_u32_e32 v2, v3
	v_sub_u32_e32 v5, 0, v3
	v_rcp_iflag_f32_e32 v2, v2
	s_nop 0
	v_mul_f32_e32 v2, 0x4f7ffffe, v2
	v_cvt_u32_f32_e32 v2, v2
	v_mul_lo_u32 v5, v5, v2
	v_mul_hi_u32 v5, v2, v5
	v_add_u32_e32 v2, v2, v5
	s_waitcnt vmcnt(0)
	v_mul_hi_u32 v2, v4, v2
	v_mul_lo_u32 v5, v2, v3
	v_sub_u32_e32 v5, v4, v5
	v_add_u32_e32 v6, 1, v2
	v_cmp_ge_u32_e32 vcc, v5, v3
	v_add_u32_e32 v4, 1, v4
	s_nop 0
	v_cndmask_b32_e32 v2, v2, v6, vcc
	v_sub_u32_e32 v6, v5, v3
	v_cndmask_b32_e32 v5, v5, v6, vcc
	v_add_u32_e32 v6, 1, v2
	v_cmp_ge_u32_e32 vcc, v5, v3
	s_nop 1
	v_cndmask_b32_e32 v2, v2, v6, vcc
	v_mul_lo_u32 v5, v3, v2
	v_add_u32_e32 v3, v5, v3
	v_cmp_ne_u32_e32 vcc, v4, v3
	s_and_saveexec_b64 s[10:11], vcc
	s_xor_b64 s[10:11], exec, s[10:11]
	s_cbranch_execz .LBB0_322
	s_bitcmp1_b32 s2, 5
	s_cbranch_scc1 .LBB0_340
	s_waitcnt lgkmcnt(0)
	v_mov_b32_e32 v1, 0x2000
	global_load_dword v1, v1, s[8:9] offset:1024 sc1
	s_add_u32 s14, s8, 0x2400
	s_addc_u32 s15, s9, 0
	s_waitcnt vmcnt(0)
	v_cmp_eq_u32_e32 vcc, v1, v2
	s_and_saveexec_b64 s[12:13], vcc
	s_cbranch_execz .LBB0_321
	s_mov_b32 s34, 1
	s_mov_b64 s[16:17], 0
	v_mov_b32_e32 v1, 0
	s_branch .LBB0_312

.LBB0_341:
	s_cmp_lt_i32 s26, 4
	s_cselect_b64 s[6:7], -1, 0
	s_and_b64 s[30:31], s[6:7], s[4:5]
	s_andn2_b64 vcc, exec, s[30:31]
	s_cbranch_vccnz .LBB0_509
	v_and_b32_e32 v2, 63, v0
	s_cmpk_gt_i32 s2, 0xff
	s_mov_b64 s[34:35], s[24:25]
	v_mov_b32_e32 v254, v2
	s_cbranch_scc1 .LBB0_383
	s_lshr_b32 s32, s2, 3
	s_and_b32 s32, s32, 7
	s_lshl_b32 s32, s32, 1
	s_lshr_b32 s32, 0x5154, s32
	s_and_b32 s32, s32, 3
	s_lshl_b32 s32, s32, 4
	s_bitcmp1_b32 s2, 5
	s_cbranch_scc0 .Lp3_go
	s_or_b32 s32, s32, 0x4000
	s_and_b32 s66, s2, 7
	s_lshr_b32 s67, s2, 3
	s_mov_b64 s[8:9], -1
	s_branch .LBB0_476
.Lp3_go:
	s_cmp_lt_u32 s32, 16
	s_cbranch_scc1 .Lconv_entry
	s_mov_b32 s11, 0
	s_mov_b64 s[4:5], exec
	s_branch .LBB0_385

.Lst_norm:
	s_ashr_i32 s6, s2, 31
	s_lshr_b32 s6, s6, 29
	s_add_i32 s6, s2, s6
	s_and_b32 s7, s6, -8
	s_ashr_i32 s5, s3, 3
	s_sub_i32 s66, s2, s7
	s_mul_i32 s5, s5, s66
	s_ashr_i32 s67, s6, 3
	s_and_b32 s4, s3, 7
	s_add_i32 s5, s5, s67
	s_cmpk_eq_i32 s3, 0x100
	s_cselect_b64 s[8:9], -1, 0
	s_cmpk_lg_i32 s3, 0x100
	s_mov_b64 s[14:15], s[24:25]
	s_cselect_b64 s[12:13], -1, 0
	s_add_u32 s68, s14, 0x5000000
	s_addc_u32 s69, s15, 0
	s_add_u32 s73, s14, 0x6000000
	s_addc_u32 s74, s15, 0
	s_add_u32 s75, s14, 0x7000000
	s_addc_u32 s76, s15, 0
	s_cmp_eq_u32 s4, 0
	s_cselect_b32 s77, s5, s2
	s_and_b32 s5, s77, 3
	s_and_b32 s6, s77, 2
	s_add_i32 s6, s6, s5
	s_and_b32 s4, s77, 4
	s_ashr_i32 s78, s77, 3
	s_sub_i32 s7, 13, s6
	s_xor_b32 s10, s5, 15
	s_sub_i32 s16, 13, s5
	s_add_i32 s17, s5, 2
	s_or_b32 s18, s5, 4
	s_cmp_lt_u32 s5, 2
	s_cselect_b32 s5, s10, s16
	s_cselect_b32 s10, s17, s18
	s_cmp_eq_u32 s4, 0
	s_cselect_b32 s79, s5, s7
	s_cselect_b32 s80, s10, s6
	s_lshr_b32 s98, s2, 3
	s_and_b32 s98, s98, 7
	s_lshr_b32 s98, 0x4, s98
	s_bitcmp1_b32 s98, 0
	s_cbranch_scc0 .Lnorev
	s_mov_b32 s98, s79
	s_mov_b32 s79, s80
	s_mov_b32 s80, s98

.LBB0_476:
	s_ashr_i32 s4, s3, 31
	s_lshr_b32 s4, s4, 29
	s_add_i32 s4, s3, s4
	v_lshlrev_b32_e32 v1, 6, v0
	s_ashr_i32 s4, s4, 3
	v_and_b32_e32 v149, 0x3c0, v1
	v_lshlrev_b32_e32 v1, 2, v0
	s_mul_i32 s20, s4, s66
	v_and_b32_e32 v147, 32, v1
	v_lshrrev_b32_e32 v1, 5, v0
	v_lshrrev_b32_e32 v3, 1, v0
	s_add_i32 s20, s20, s67
	v_and_b32_e32 v1, 4, v1
	v_bfe_u32 v2, v0, 2, 2
	v_and_b32_e32 v142, 24, v3
	s_and_b32 s22, s20, 3
	v_or3_b32 v1, v1, v2, v142
	v_lshlrev_b32_e32 v2, 4, v0
	s_bitcmp0_b32 s20, 2
	v_or_b32_e32 v145, 0x2000, v2
	s_cselect_b64 s[4:5], -1, 0
	v_lshrrev_b32_e32 v3, 7, v145
	s_movk_i32 s6, 0x60
	v_and_b32_e32 v4, 32, v0
	s_and_b64 s[4:5], s[8:9], s[4:5]
	v_and_or_b32 v150, v3, s6, v1
	v_bitop3_b32 v143, v2, v4, 48 bitop3:0x6c
	v_and_b32_e32 v144, 64, v0
	v_bfe_u32 v146, v0, 2, 4
	s_movk_i32 s6, 0x70
	v_lshrrev_b32_e32 v2, 3, v0
	v_and_b32_e32 v148, 15, v0
	v_or_b32_e32 v151, v143, v144
	v_and_or_b32 v152, v3, s6, v146
	v_and_or_b32 v153, v2, 32, v1
	v_and_or_b32 v154, v2, 48, v146
	s_mov_b64 s[6:7], s[24:25]
	s_andn2_b64 vcc, exec, s[4:5]
	s_mov_b64 s[4:5], -1
	s_cbranch_vccz .LBB0_494
	s_andn2_b64 vcc, exec, s[8:9]
	s_cbranch_vccnz .LBB0_493
	s_bitcmp1_b32 s32, 14
	s_cbranch_scc1 .Lb_cont2
	s_cmp_lg_u32 s32, 32
	s_cbranch_scc1 .Lb_cont
	s_mov_b32 s32, 33
	v_and_b32_e32 v2, 63, v0
	v_or_b32_e32 v194, 0x400, v0
	v_or_b32_e32 v195, 0x800, v0
	v_or_b32_e32 v211, 0xc00, v0
	v_and_b32_e32 v254, 63, v0
	s_mov_b64 s[34:35], s[24:25]
	s_branch .Lconv_entry

.Lb_cont2:
	s_bitcmp1_b32 s32, 14
	s_cbranch_scc0 .LBB0_493
	s_ashr_i32 s21, s20, 1
	s_cmpk_gt_u32 s21, 0x7f
	v_readfirstlane_b32 s23, v0
	s_cbranch_scc1 .LBB0_486
	s_lshr_b32 s11, s23, 6
	s_or_b32 s34, s22, 12
	s_lshr_b32 s35, s21, 2
	s_lshr_b32 s10, s23, 8
	s_lshl_b32 s16, s11, 10
	s_lshl_b32 s12, s35, 20
	s_lshl_b32 s4, s34, 20
	s_add_u32 s8, s6, s4
	s_addc_u32 s9, s7, 0
	s_add_u32 s4, s8, 0x200000
	s_addc_u32 s5, s9, 0
	s_add_i32 s36, s16, 0
	v_lshl_or_b32 v134, v153, 12, v151
	s_add_i32 m0, s36, 0x10000
	v_lshl_or_b32 v130, v150, 12, v151
	global_load_lds_dwordx4 v134, s[4:5]
	s_add_i32 m0, s36, 0x12000
	s_add_u32 s8, s8, 0x280000
	global_load_lds_dwordx4 v130, s[4:5]
	s_addc_u32 s9, s9, 0
	s_add_i32 m0, s36, 0x14000
	v_lshl_or_b32 v136, v154, 12, v151
	global_load_lds_dwordx4 v134, s[8:9]
	s_add_i32 m0, s36, 0x16000
	s_add_u32 s13, s6, s12
	s_addc_u32 s15, s7, 0
	global_load_lds_dwordx4 v130, s[8:9]
	s_add_u32 s8, s13, 0x3000000
	s_addc_u32 s9, s15, 0
	s_add_i32 s37, s36, 0x2000
	s_mov_b32 m0, s36
	s_add_u32 s14, s13, 0x3080000
	v_lshl_or_b32 v132, v152, 12, v151
	global_load_lds_dwordx4 v136, s[8:9]
	s_mov_b32 m0, s37
	s_addc_u32 s15, s15, 0
	s_add_i32 s38, s36, 0x4000
	global_load_lds_dwordx4 v132, s[8:9]
	s_mov_b32 m0, s38
	s_add_i32 s39, s36, 0x6000
	global_load_lds_dwordx4 v136, s[14:15]
	s_mov_b32 m0, s39
	v_mov_b32_e32 v135, 0
	global_load_lds_dwordx4 v132, s[14:15]
	v_mov_b32_e32 v131, v135
	v_mov_b32_e32 v137, v135
	v_mov_b32_e32 v133, v135
	v_lshl_add_u64 v[8:9], s[4:5], 0, v[134:135]
	v_lshl_add_u64 v[6:7], s[4:5], 0, v[130:131]
	v_lshl_add_u64 v[4:5], s[8:9], 0, v[136:137]
	s_cmp_lg_u32 s10, 1
	v_lshl_add_u64 v[2:3], s[8:9], 0, v[132:133]
	s_cbranch_scc1 .LBB0_481
	s_barrier

.LBB0_494:
	s_bitcmp1_b32 s32, 14
	s_cbranch_scc0 .Lno_pregate
	s_andn2_b32 s32, s32, 0x4000
	s_mov_b64 s[98:99], exec
	v_cmp_eq_u32_e64 s[100:101], 0, v0
	s_and_b64 exec, exec, s[100:101]
	s_cbranch_execz .Lpg_rest
	s_lshl_b32 s66, s33, 8
	s_add_i32 s66, s66, 0x2400
	v_mov_b32_e32 v1, s66
	s_mov_b32 s67, 0
.Lpg_spin:
	global_load_dword v2, v1, s[24:25] sc1
	s_waitcnt vmcnt(0)
	v_readfirstlane_b32 s66, v2
	s_nop 3
	s_cmp_ge_u32 s66, 2
	s_cbranch_scc1 .Lpg_done
	s_sleep 1
	s_add_i32 s67, s67, 1
	s_cmp_lt_u32 s67, 0x40000
	s_cbranch_scc1 .Lpg_spin

.Lpg_rest:
	s_mov_b64 exec, s[98:99]
	s_waitcnt vmcnt(0) lgkmcnt(0)
	s_barrier
	v_and_b32_e32 v2, 63, v0
	v_or_b32_e32 v194, 0x400, v0
	v_or_b32_e32 v195, 0x800, v0
	v_or_b32_e32 v211, 0xc00, v0
	v_and_b32_e32 v254, 63, v0
	s_mov_b64 s[34:35], s[24:25]
	s_branch .Lp3_go
